# baseline (speedup 1.0000x reference)
.LBB0_490:
	v_readfirstlane_b32 s98, v218
	s_nop 3
	s_lshr_b32 s98, s98, 6
	s_cmp_ge_u32 s98, 4
	s_cbranch_scc0 .Lprio_skip
	s_setprio 1

.LBB0_549:
	s_setprio 0
	s_waitcnt vmcnt(0)
	s_barrier
	s_waitcnt vmcnt(0)
	s_barrier
	s_mov_b64 s[0:1], exec
	v_readlane_b32 s2, v252, 22
	v_readlane_b32 s3, v252, 23
	v_readlane_b32 s44, v252, 50
	s_and_b64 s[2:3], s[0:1], s[2:3]
	v_readlane_b32 s45, v252, 51
	s_mov_b64 exec, s[2:3]
	s_cbranch_execz .LBB0_601
	v_mov_b32_e32 v4, 0x22000
	ds_read_b32 v5, v4
	ds_read_b32 v6, v4 offset:4
	v_readlane_b32 s3, v252, 21
	s_nop 3
	s_lshl_b32 s3, s3, 8
	s_add_i32 s3, s3, 0x80
	v_mov_b32_e32 v0, s3
	v_mov_b32_e32 v1, 1
	s_add_u32 s4, s60, 0x1400
	s_addc_u32 s5, s61, 0
	global_atomic_add v2, v0, v1, s[4:5] sc0
	s_add_u32 s4, s60, 0x2400
	s_addc_u32 s5, s61, 0
	s_waitcnt vmcnt(0) lgkmcnt(0)
	v_readfirstlane_b32 s2, v2
	v_readfirstlane_b32 s12, v5
	v_readfirstlane_b32 s13, v6
	s_nop 3
	s_mul_i32 s12, s12, 2
	s_mul_i32 s13, s13, 2
	s_add_i32 s2, s2, 1
	s_cmp_lg_u32 s2, s12
	s_cbranch_scc1 .Lmf2_poll
	buffer_wbl2 sc1
	s_waitcnt vmcnt(0)
	v_mov_b32_e32 v3, 0
	s_add_u32 s2, s60, 0x3480
	s_addc_u32 s3, s61, 0
	global_atomic_add v2, v3, v1, s[2:3] sc0
	s_waitcnt vmcnt(0)
	v_readfirstlane_b32 s2, v2
	s_nop 3
	s_add_i32 s2, s2, 1
	s_cmp_lg_u32 s2, s13
	s_cbranch_scc1 .Lmf2_poll
	v_mov_b32_e32 v3, 0x80
	global_atomic_add v3, v1, s[4:5]
	global_atomic_add v3, v1, s[4:5] offset:256
	global_atomic_add v3, v1, s[4:5] offset:512
	global_atomic_add v3, v1, s[4:5] offset:768
	global_atomic_add v3, v1, s[4:5] offset:1024
	global_atomic_add v3, v1, s[4:5] offset:1280
	global_atomic_add v3, v1, s[4:5] offset:1536
	global_atomic_add v3, v1, s[4:5] offset:1792
	global_atomic_add v3, v1, s[4:5] offset:2048
	global_atomic_add v3, v1, s[4:5] offset:2304
	global_atomic_add v3, v1, s[4:5] offset:2560
	global_atomic_add v3, v1, s[4:5] offset:2816
	global_atomic_add v3, v1, s[4:5] offset:3072
	global_atomic_add v3, v1, s[4:5] offset:3328
	global_atomic_add v3, v1, s[4:5] offset:3584
	global_atomic_add v3, v1, s[4:5] offset:3840
